# LayerNorm bf16 (next-GEMM operand) stores also marked nt (streaming) in addition to sc1
# baseline (speedup 1.0000x reference)
; DI float bflo(unsigned u) { return __uint_as_float(u << 16); }
; DI float bfhi(unsigned u) { return __uint_as_float(u & 0xffff0000u); }
; template <int NR>
; DI void ln_rows(const Params& P, const LnSpec& sp, int row, int stride, int lane) {
;     ...
;     for (int k = 0; k < NR; ++k) {
;         const int r = row + k * stride;
;         const float* xp = r < RL ? sp.res_lat + (size_t)r * 1024 : sp.res_ctx + (size_t)(r - RL) * 1024;
;         const bf16_t* yp = sp.Y + (size_t)r * 1024;
; #pragma unroll
;         for (int i = 0; i < 4; ++i) {
;             const f32x4 x = __builtin_nontemporal_load((const f32x4*)(xp + (i * 64 + lane) * 4));
;             const u32x2 y = __builtin_nontemporal_load((const u32x2*)(yp + (i * 64 + lane) * 4));
;             v[k][i][0] = ALPHA * x[0] + bflo(y.x); v[k][i][1] = ALPHA * x[1] + bfhi(y.x);
;             v[k][i][2] = ALPHA * x[2] + bflo(y.y); v[k][i][3] = ALPHA * x[3] + bfhi(y.y);
;         }
;     }
; #pragma unroll
;     for (int k = 0; k < NR; ++k) {
;         s[k] = 0.f;
; #pragma unroll
;         for (int i = 0; i < 4; ++i) s[k] += (v[k][i][0] + v[k][i][1]) + (v[k][i][2] + v[k][i][3]);
;     }
.Lmy_ln1_row0:
	s_cmp_eq_u32 s18, 1
	s_cselect_b32 s3, 0, 0x4f83200
	s_add_u32 s3, s3, s2
	v_add_u32_e32 v218, s3, v170
	s_add_u32 s3, s3, 0x1000
	v_add_u32_e32 v219, s3, v170
	s_add_u32 s3, s3, 0x1000
	v_add_u32_e32 v220, s3, v170
	s_add_u32 s3, s3, 0x1000
	v_add_u32_e32 v221, s3, v170
	s_lshr_b32 s3, s2, 1
	s_add_u32 s3, s3, 0xd383200
	v_add_u32_e32 v222, s3, v171
	s_add_u32 s3, s3, 0x1000
	v_add_u32_e32 v223, s3, v171
	v_lshlrev_b32_e32 v224, 16, v64
	v_and_b32_e32 v225, 0xffff0000, v64
	v_fmamk_f32 v0, v0, 0x3fb504f3, v224
	v_fmamk_f32 v1, v1, 0x3fb504f3, v225
	v_lshlrev_b32_e32 v224, 16, v65
	v_and_b32_e32 v225, 0xffff0000, v65
	v_fmamk_f32 v2, v2, 0x3fb504f3, v224
	v_fmamk_f32 v3, v3, 0x3fb504f3, v225
	v_add_f32_e32 v226, v0, v1
	v_add_f32_e32 v227, v2, v3
	v_add_f32_e32 v226, v226, v227
	v_mov_b32_e32 v166, v226
	v_lshlrev_b32_e32 v224, 16, v66
	v_and_b32_e32 v225, 0xffff0000, v66
	v_fmamk_f32 v4, v4, 0x3fb504f3, v224
	v_fmamk_f32 v5, v5, 0x3fb504f3, v225
	v_lshlrev_b32_e32 v224, 16, v67
	v_and_b32_e32 v225, 0xffff0000, v67
	v_fmamk_f32 v6, v6, 0x3fb504f3, v224
	v_fmamk_f32 v7, v7, 0x3fb504f3, v225
	v_add_f32_e32 v226, v4, v5
	v_add_f32_e32 v227, v6, v7
	v_add_f32_e32 v226, v226, v227
	v_add_f32_e32 v166, v166, v226
	v_lshlrev_b32_e32 v224, 16, v68
	v_and_b32_e32 v225, 0xffff0000, v68
	v_fmamk_f32 v8, v8, 0x3fb504f3, v224
	v_fmamk_f32 v9, v9, 0x3fb504f3, v225
	v_lshlrev_b32_e32 v224, 16, v69
	v_and_b32_e32 v225, 0xffff0000, v69
	v_fmamk_f32 v10, v10, 0x3fb504f3, v224
	v_fmamk_f32 v11, v11, 0x3fb504f3, v225
	v_add_f32_e32 v226, v8, v9
	v_add_f32_e32 v227, v10, v11
	v_add_f32_e32 v226, v226, v227
	v_add_f32_e32 v166, v166, v226
	v_lshlrev_b32_e32 v224, 16, v70
	v_and_b32_e32 v225, 0xffff0000, v70
	v_fmamk_f32 v12, v12, 0x3fb504f3, v224
	v_fmamk_f32 v13, v13, 0x3fb504f3, v225
	v_lshlrev_b32_e32 v224, 16, v71
	v_and_b32_e32 v225, 0xffff0000, v71
	v_fmamk_f32 v14, v14, 0x3fb504f3, v224
	v_fmamk_f32 v15, v15, 0x3fb504f3, v225
	v_add_f32_e32 v226, v12, v13
	v_add_f32_e32 v227, v14, v15
	v_add_f32_e32 v226, v226, v227
	v_add_f32_e32 v166, v166, v226
	s_waitcnt vmcnt(16)
	v_lshlrev_b32_e32 v224, 16, v72
	v_and_b32_e32 v225, 0xffff0000, v72
	v_fmamk_f32 v16, v16, 0x3fb504f3, v224
	v_fmamk_f32 v17, v17, 0x3fb504f3, v225
	v_lshlrev_b32_e32 v224, 16, v73
	v_and_b32_e32 v225, 0xffff0000, v73
	v_fmamk_f32 v18, v18, 0x3fb504f3, v224
	v_fmamk_f32 v19, v19, 0x3fb504f3, v225
	v_add_f32_e32 v226, v16, v17
	v_add_f32_e32 v227, v18, v19
	v_add_f32_e32 v226, v226, v227
	v_mov_b32_e32 v167, v226
	v_lshlrev_b32_e32 v224, 16, v74
	v_and_b32_e32 v225, 0xffff0000, v74
	v_fmamk_f32 v20, v20, 0x3fb504f3, v224
	v_fmamk_f32 v21, v21, 0x3fb504f3, v225
	v_lshlrev_b32_e32 v224, 16, v75
	v_and_b32_e32 v225, 0xffff0000, v75
	v_fmamk_f32 v22, v22, 0x3fb504f3, v224
	v_fmamk_f32 v23, v23, 0x3fb504f3, v225
	v_add_f32_e32 v226, v20, v21
	v_add_f32_e32 v227, v22, v23
	v_add_f32_e32 v226, v226, v227
	v_add_f32_e32 v167, v167, v226
	v_lshlrev_b32_e32 v224, 16, v76
	v_and_b32_e32 v225, 0xffff0000, v76
	v_fmamk_f32 v24, v24, 0x3fb504f3, v224
	v_fmamk_f32 v25, v25, 0x3fb504f3, v225
	v_lshlrev_b32_e32 v224, 16, v77
	v_and_b32_e32 v225, 0xffff0000, v77
	v_fmamk_f32 v26, v26, 0x3fb504f3, v224
	v_fmamk_f32 v27, v27, 0x3fb504f3, v225
	v_add_f32_e32 v226, v24, v25
	v_add_f32_e32 v227, v26, v27
	v_add_f32_e32 v226, v226, v227
	v_add_f32_e32 v167, v167, v226
	v_lshlrev_b32_e32 v224, 16, v78
	v_and_b32_e32 v225, 0xffff0000, v78
	v_fmamk_f32 v28, v28, 0x3fb504f3, v224
	v_fmamk_f32 v29, v29, 0x3fb504f3, v225
	v_lshlrev_b32_e32 v224, 16, v79
	v_and_b32_e32 v225, 0xffff0000, v79
	v_fmamk_f32 v30, v30, 0x3fb504f3, v224
	v_fmamk_f32 v31, v31, 0x3fb504f3, v225
	v_add_f32_e32 v226, v28, v29
	v_add_f32_e32 v227, v30, v31
	v_add_f32_e32 v226, v226, v227
	v_add_f32_e32 v167, v167, v226
	s_waitcnt vmcnt(8)
	v_lshlrev_b32_e32 v224, 16, v80
	v_and_b32_e32 v225, 0xffff0000, v80
	v_fmamk_f32 v32, v32, 0x3fb504f3, v224
	v_fmamk_f32 v33, v33, 0x3fb504f3, v225
	v_lshlrev_b32_e32 v224, 16, v81
	v_and_b32_e32 v225, 0xffff0000, v81
	v_fmamk_f32 v34, v34, 0x3fb504f3, v224
	v_fmamk_f32 v35, v35, 0x3fb504f3, v225
	v_add_f32_e32 v226, v32, v33
	v_add_f32_e32 v227, v34, v35
	v_add_f32_e32 v226, v226, v227
	v_mov_b32_e32 v168, v226
	v_lshlrev_b32_e32 v224, 16, v82
	v_and_b32_e32 v225, 0xffff0000, v82
	v_fmamk_f32 v36, v36, 0x3fb504f3, v224
	v_fmamk_f32 v37, v37, 0x3fb504f3, v225
	v_lshlrev_b32_e32 v224, 16, v83
	v_and_b32_e32 v225, 0xffff0000, v83
	v_fmamk_f32 v38, v38, 0x3fb504f3, v224
	v_fmamk_f32 v39, v39, 0x3fb504f3, v225
	v_add_f32_e32 v226, v36, v37
	v_add_f32_e32 v227, v38, v39
	v_add_f32_e32 v226, v226, v227
	v_add_f32_e32 v168, v168, v226
	v_lshlrev_b32_e32 v224, 16, v84
	v_and_b32_e32 v225, 0xffff0000, v84
	v_fmamk_f32 v40, v40, 0x3fb504f3, v224
	v_fmamk_f32 v41, v41, 0x3fb504f3, v225
	v_lshlrev_b32_e32 v224, 16, v85
	v_and_b32_e32 v225, 0xffff0000, v85
	v_fmamk_f32 v42, v42, 0x3fb504f3, v224
	v_fmamk_f32 v43, v43, 0x3fb504f3, v225
	v_add_f32_e32 v226, v40, v41
	v_add_f32_e32 v227, v42, v43
	v_add_f32_e32 v226, v226, v227
	v_add_f32_e32 v168, v168, v226
	v_lshlrev_b32_e32 v224, 16, v86
	v_and_b32_e32 v225, 0xffff0000, v86
	v_fmamk_f32 v44, v44, 0x3fb504f3, v224
	v_fmamk_f32 v45, v45, 0x3fb504f3, v225
	v_lshlrev_b32_e32 v224, 16, v87
	v_and_b32_e32 v225, 0xffff0000, v87
	v_fmamk_f32 v46, v46, 0x3fb504f3, v224
	v_fmamk_f32 v47, v47, 0x3fb504f3, v225
	v_add_f32_e32 v226, v44, v45
	v_add_f32_e32 v227, v46, v47
	v_add_f32_e32 v226, v226, v227
	v_add_f32_e32 v168, v168, v226
	s_waitcnt vmcnt(0)
; template <int NR>
; DI void ln_rows(const Params& P, const LnSpec& sp, int row, int stride, int lane) {
;     ...
;     for (int k = 0; k < NR; ++k) {
;         s[k] = 0.f;
; #pragma unroll
;         for (int i = 0; i < 4; ++i) s[k] += (v[k][i][0] + v[k][i][1]) + (v[k][i][2] + v[k][i][3]);
;     }
; #pragma unroll
;     for (int o = 32; o >= 1; o >>= 1)
; #pragma unroll
;         for (int k = 0; k < NR; ++k) s[k] += __shfl_xor(s[k], o);
; #pragma unroll
;     for (int k = 0; k < NR; ++k) {
;         s[k] *= (1.f / 1024.f); qv[k] = 0.f;
; #pragma unroll
;         for (int i = 0; i < 4; ++i)
; #pragma unroll
;             for (int j = 0; j < 4; ++j) { const float d = v[k][i][j] - s[k]; qv[k] += d * d; }
	v_lshlrev_b32_e32 v224, 16, v88
	v_and_b32_e32 v225, 0xffff0000, v88
	v_fmamk_f32 v48, v48, 0x3fb504f3, v224
	v_fmamk_f32 v49, v49, 0x3fb504f3, v225
	v_lshlrev_b32_e32 v224, 16, v89
	v_and_b32_e32 v225, 0xffff0000, v89
	v_fmamk_f32 v50, v50, 0x3fb504f3, v224
	v_fmamk_f32 v51, v51, 0x3fb504f3, v225
	v_add_f32_e32 v226, v48, v49
	v_add_f32_e32 v227, v50, v51
	v_add_f32_e32 v226, v226, v227
	v_mov_b32_e32 v169, v226
	v_lshlrev_b32_e32 v224, 16, v90
	v_and_b32_e32 v225, 0xffff0000, v90
	v_fmamk_f32 v52, v52, 0x3fb504f3, v224
	v_fmamk_f32 v53, v53, 0x3fb504f3, v225
	v_lshlrev_b32_e32 v224, 16, v91
	v_and_b32_e32 v225, 0xffff0000, v91
	v_fmamk_f32 v54, v54, 0x3fb504f3, v224
	v_fmamk_f32 v55, v55, 0x3fb504f3, v225
	v_add_f32_e32 v226, v52, v53
	v_add_f32_e32 v227, v54, v55
	v_add_f32_e32 v226, v226, v227
	v_add_f32_e32 v169, v169, v226
	v_lshlrev_b32_e32 v224, 16, v92
	v_and_b32_e32 v225, 0xffff0000, v92
	v_fmamk_f32 v56, v56, 0x3fb504f3, v224
	v_fmamk_f32 v57, v57, 0x3fb504f3, v225
	v_lshlrev_b32_e32 v224, 16, v93
	v_and_b32_e32 v225, 0xffff0000, v93
	v_fmamk_f32 v58, v58, 0x3fb504f3, v224
	v_fmamk_f32 v59, v59, 0x3fb504f3, v225
	v_add_f32_e32 v226, v56, v57
	v_add_f32_e32 v227, v58, v59
	v_add_f32_e32 v226, v226, v227
	v_add_f32_e32 v169, v169, v226
	v_lshlrev_b32_e32 v224, 16, v94
	v_and_b32_e32 v225, 0xffff0000, v94
	v_fmamk_f32 v60, v60, 0x3fb504f3, v224
	v_fmamk_f32 v61, v61, 0x3fb504f3, v225
	v_lshlrev_b32_e32 v224, 16, v95
	v_and_b32_e32 v225, 0xffff0000, v95
	v_fmamk_f32 v62, v62, 0x3fb504f3, v224
	v_fmamk_f32 v63, v63, 0x3fb504f3, v225
	v_add_f32_e32 v226, v60, v61
	v_add_f32_e32 v227, v62, v63
	v_add_f32_e32 v226, v226, v227
	v_add_f32_e32 v169, v169, v226
	ds_bpermute_b32 v178, v160, v166
	ds_bpermute_b32 v179, v160, v167
	ds_bpermute_b32 v180, v160, v168
	ds_bpermute_b32 v181, v160, v169
	s_waitcnt lgkmcnt(0)
	v_add_f32_e32 v166, v166, v178
	v_add_f32_e32 v167, v167, v179
	v_add_f32_e32 v168, v168, v180
	v_add_f32_e32 v169, v169, v181
	ds_bpermute_b32 v178, v161, v166
	ds_bpermute_b32 v179, v161, v167
	ds_bpermute_b32 v180, v161, v168
	ds_bpermute_b32 v181, v161, v169
	s_waitcnt lgkmcnt(0)
	v_add_f32_e32 v166, v166, v178
	v_add_f32_e32 v167, v167, v179
	v_add_f32_e32 v168, v168, v180
	v_add_f32_e32 v169, v169, v181
	ds_bpermute_b32 v178, v162, v166
	ds_bpermute_b32 v179, v162, v167
	ds_bpermute_b32 v180, v162, v168
	ds_bpermute_b32 v181, v162, v169
	s_waitcnt lgkmcnt(0)
	v_add_f32_e32 v166, v166, v178
	v_add_f32_e32 v167, v167, v179
	v_add_f32_e32 v168, v168, v180
	v_add_f32_e32 v169, v169, v181
	ds_bpermute_b32 v178, v163, v166
	ds_bpermute_b32 v179, v163, v167
	ds_bpermute_b32 v180, v163, v168
	ds_bpermute_b32 v181, v163, v169
	s_waitcnt lgkmcnt(0)
	v_add_f32_e32 v166, v166, v178
	v_add_f32_e32 v167, v167, v179
	v_add_f32_e32 v168, v168, v180
	v_add_f32_e32 v169, v169, v181
	ds_bpermute_b32 v178, v164, v166
	ds_bpermute_b32 v179, v164, v167
	ds_bpermute_b32 v180, v164, v168
	ds_bpermute_b32 v181, v164, v169
	s_waitcnt lgkmcnt(0)
	v_add_f32_e32 v166, v166, v178
	v_add_f32_e32 v167, v167, v179
	v_add_f32_e32 v168, v168, v180
	v_add_f32_e32 v169, v169, v181
	ds_bpermute_b32 v178, v165, v166
	ds_bpermute_b32 v179, v165, v167
	ds_bpermute_b32 v180, v165, v168
	ds_bpermute_b32 v181, v165, v169
	s_waitcnt lgkmcnt(0)
	v_add_f32_e32 v166, v166, v178
	v_add_f32_e32 v167, v167, v179
	v_add_f32_e32 v168, v168, v180
	v_add_f32_e32 v169, v169, v181
	v_mul_f32_e32 v166, 0x3a800000, v166
	v_mul_f32_e32 v167, 0x3a800000, v167
	v_mul_f32_e32 v168, 0x3a800000, v168
	v_mul_f32_e32 v169, 0x3a800000, v169
	v_mov_b32_e32 v174, 0
	v_sub_f32_e32 v0, v0, v166
	v_fmac_f32_e32 v174, v0, v0
	v_sub_f32_e32 v1, v1, v166
	v_fmac_f32_e32 v174, v1, v1
	v_sub_f32_e32 v2, v2, v166
	v_fmac_f32_e32 v174, v2, v2
	v_sub_f32_e32 v3, v3, v166
	v_fmac_f32_e32 v174, v3, v3
	v_sub_f32_e32 v4, v4, v166
	v_fmac_f32_e32 v174, v4, v4
	v_sub_f32_e32 v5, v5, v166
	v_fmac_f32_e32 v174, v5, v5
	v_sub_f32_e32 v6, v6, v166
	v_fmac_f32_e32 v174, v6, v6
	v_sub_f32_e32 v7, v7, v166
	v_fmac_f32_e32 v174, v7, v7
	v_sub_f32_e32 v8, v8, v166
	v_fmac_f32_e32 v174, v8, v8
	v_sub_f32_e32 v9, v9, v166
	v_fmac_f32_e32 v174, v9, v9
	v_sub_f32_e32 v10, v10, v166
	v_fmac_f32_e32 v174, v10, v10
	v_sub_f32_e32 v11, v11, v166
	v_fmac_f32_e32 v174, v11, v11
	v_sub_f32_e32 v12, v12, v166
	v_fmac_f32_e32 v174, v12, v12
	v_sub_f32_e32 v13, v13, v166
	v_fmac_f32_e32 v174, v13, v13
	v_sub_f32_e32 v14, v14, v166
	v_fmac_f32_e32 v174, v14, v14
	v_sub_f32_e32 v15, v15, v166
	v_fmac_f32_e32 v174, v15, v15
	v_mov_b32_e32 v175, 0
	v_sub_f32_e32 v16, v16, v167
	v_fmac_f32_e32 v175, v16, v16
	v_sub_f32_e32 v17, v17, v167
	v_fmac_f32_e32 v175, v17, v17
	v_sub_f32_e32 v18, v18, v167
	v_fmac_f32_e32 v175, v18, v18
	v_sub_f32_e32 v19, v19, v167
	v_fmac_f32_e32 v175, v19, v19
	v_sub_f32_e32 v20, v20, v167
	v_fmac_f32_e32 v175, v20, v20
	v_sub_f32_e32 v21, v21, v167
	v_fmac_f32_e32 v175, v21, v21
	v_sub_f32_e32 v22, v22, v167
	v_fmac_f32_e32 v175, v22, v22
	v_sub_f32_e32 v23, v23, v167
	v_fmac_f32_e32 v175, v23, v23
	v_sub_f32_e32 v24, v24, v167
	v_fmac_f32_e32 v175, v24, v24
	v_sub_f32_e32 v25, v25, v167
	v_fmac_f32_e32 v175, v25, v25
	v_sub_f32_e32 v26, v26, v167
	v_fmac_f32_e32 v175, v26, v26
	v_sub_f32_e32 v27, v27, v167
	v_fmac_f32_e32 v175, v27, v27
	v_sub_f32_e32 v28, v28, v167
	v_fmac_f32_e32 v175, v28, v28
	v_sub_f32_e32 v29, v29, v167
	v_fmac_f32_e32 v175, v29, v29
	v_sub_f32_e32 v30, v30, v167
	v_fmac_f32_e32 v175, v30, v30
	v_sub_f32_e32 v31, v31, v167
	v_fmac_f32_e32 v175, v31, v31
	v_mov_b32_e32 v176, 0
	v_sub_f32_e32 v32, v32, v168
	v_fmac_f32_e32 v176, v32, v32
	v_sub_f32_e32 v33, v33, v168
; DI unsigned pk2(float a, float b) { f32x2 v = {a, b}; bfx2 r = __builtin_convertvector(v, bfx2); return __builtin_bit_cast(unsigned, r); }
; template <int NR>
; DI void ln_rows(const Params& P, const LnSpec& sp, int row, int stride, int lane) {
;     ...
;     for (int k = 0; k < NR; ++k) {
;         s[k] *= (1.f / 1024.f); qv[k] = 0.f;
; #pragma unroll
;         for (int i = 0; i < 4; ++i)
; #pragma unroll
;             for (int j = 0; j < 4; ++j) { const float d = v[k][i][j] - s[k]; qv[k] += d * d; }
;     }
; #pragma unroll
;     for (int o = 32; o >= 1; o >>= 1)
; #pragma unroll
;         for (int k = 0; k < NR; ++k) qv[k] += __shfl_xor(qv[k], o);
; #pragma unroll
;     for (int k = 0; k < NR; ++k) {
;         const int r = row + k * stride;
;         const float mu = s[k], rstd = rsqrtf(qv[k] * (1.f / 1024.f) + 1e-6f);
;         const int sidx = r < RL ? (r >> 13) : 4;
;         const float* sh = MOD + (size_t)(sp.lnext * 5 + sidx) * 9216 + sp.mshift * 1024; const float* scl = sh + 1024;
;         float* xp = X + (size_t)r * 1024;
; #pragma unroll
;         for (int i = 0; i < 4; ++i) {
;             const int c = (i * 64 + lane) * 4;
;             const f32x4 gg = *(const f32x4*)(g + c), b4 = *(const f32x4*)(bb + c);
;             f32x4 y;
; #pragma unroll
;             for (int j = 0; j < 4; ++j) y[j] = (v[k][i][j] - mu) * rstd * gg[j] + b4[j];
;             if (sp.final_) { __builtin_nontemporal_store(y, (f32x4*)(P.out + (size_t)r * 1024 + c)); }
;             else {
;                 __builtin_nontemporal_store(y, (f32x4*)(xp + c));
;                 const f32x4 a = *(const f32x4*)(sh + c), sg = *(const f32x4*)(scl + c);
;                 u32x2 w; w.x = pk2(y[0] * (1.f + sg[0]) + a[0], y[1] * (1.f + sg[1]) + a[1]); w.y = pk2(y[2] * (1.f + sg[2]) + a[2], y[3] * (1.f + sg[3]) + a[3]);
;                 *(u32x2*)(XM + (size_t)r * 1024 + c) = w;
;             }
;         }
;     }
	v_fmac_f32_e32 v176, v33, v33
	v_sub_f32_e32 v34, v34, v168
	v_fmac_f32_e32 v176, v34, v34
	v_sub_f32_e32 v35, v35, v168
	v_fmac_f32_e32 v176, v35, v35
	v_sub_f32_e32 v36, v36, v168
	v_fmac_f32_e32 v176, v36, v36
	v_sub_f32_e32 v37, v37, v168
	v_fmac_f32_e32 v176, v37, v37
	v_sub_f32_e32 v38, v38, v168
	v_fmac_f32_e32 v176, v38, v38
	v_sub_f32_e32 v39, v39, v168
	v_fmac_f32_e32 v176, v39, v39
	v_sub_f32_e32 v40, v40, v168
	v_fmac_f32_e32 v176, v40, v40
	v_sub_f32_e32 v41, v41, v168
	v_fmac_f32_e32 v176, v41, v41
	v_sub_f32_e32 v42, v42, v168
	v_fmac_f32_e32 v176, v42, v42
	v_sub_f32_e32 v43, v43, v168
	v_fmac_f32_e32 v176, v43, v43
	v_sub_f32_e32 v44, v44, v168
	v_fmac_f32_e32 v176, v44, v44
	v_sub_f32_e32 v45, v45, v168
	v_fmac_f32_e32 v176, v45, v45
	v_sub_f32_e32 v46, v46, v168
	v_fmac_f32_e32 v176, v46, v46
	v_sub_f32_e32 v47, v47, v168
	v_fmac_f32_e32 v176, v47, v47
	v_mov_b32_e32 v177, 0
	v_sub_f32_e32 v48, v48, v169
	v_fmac_f32_e32 v177, v48, v48
	v_sub_f32_e32 v49, v49, v169
	v_fmac_f32_e32 v177, v49, v49
	v_sub_f32_e32 v50, v50, v169
	v_fmac_f32_e32 v177, v50, v50
	v_sub_f32_e32 v51, v51, v169
	v_fmac_f32_e32 v177, v51, v51
	v_sub_f32_e32 v52, v52, v169
	v_fmac_f32_e32 v177, v52, v52
	v_sub_f32_e32 v53, v53, v169
	v_fmac_f32_e32 v177, v53, v53
	v_sub_f32_e32 v54, v54, v169
	v_fmac_f32_e32 v177, v54, v54
	v_sub_f32_e32 v55, v55, v169
	v_fmac_f32_e32 v177, v55, v55
	v_sub_f32_e32 v56, v56, v169
	v_fmac_f32_e32 v177, v56, v56
	v_sub_f32_e32 v57, v57, v169
	v_fmac_f32_e32 v177, v57, v57
	v_sub_f32_e32 v58, v58, v169
	v_fmac_f32_e32 v177, v58, v58
	v_sub_f32_e32 v59, v59, v169
	v_fmac_f32_e32 v177, v59, v59
	v_sub_f32_e32 v60, v60, v169
	v_fmac_f32_e32 v177, v60, v60
	v_sub_f32_e32 v61, v61, v169
	v_fmac_f32_e32 v177, v61, v61
	v_sub_f32_e32 v62, v62, v169
	v_fmac_f32_e32 v177, v62, v62
	v_sub_f32_e32 v63, v63, v169
	v_fmac_f32_e32 v177, v63, v63
	ds_bpermute_b32 v178, v160, v174
	ds_bpermute_b32 v179, v160, v175
	ds_bpermute_b32 v180, v160, v176
	ds_bpermute_b32 v181, v160, v177
	s_waitcnt lgkmcnt(0)
	v_add_f32_e32 v174, v174, v178
	v_add_f32_e32 v175, v175, v179
	v_add_f32_e32 v176, v176, v180
	v_add_f32_e32 v177, v177, v181
	ds_bpermute_b32 v178, v161, v174
	ds_bpermute_b32 v179, v161, v175
	ds_bpermute_b32 v180, v161, v176
	ds_bpermute_b32 v181, v161, v177
	s_waitcnt lgkmcnt(0)
	v_add_f32_e32 v174, v174, v178
	v_add_f32_e32 v175, v175, v179
	v_add_f32_e32 v176, v176, v180
	v_add_f32_e32 v177, v177, v181
	ds_bpermute_b32 v178, v162, v174
	ds_bpermute_b32 v179, v162, v175
	ds_bpermute_b32 v180, v162, v176
	ds_bpermute_b32 v181, v162, v177
	s_waitcnt lgkmcnt(0)
	v_add_f32_e32 v174, v174, v178
	v_add_f32_e32 v175, v175, v179
	v_add_f32_e32 v176, v176, v180
	v_add_f32_e32 v177, v177, v181
	ds_bpermute_b32 v178, v163, v174
	ds_bpermute_b32 v179, v163, v175
	ds_bpermute_b32 v180, v163, v176
	ds_bpermute_b32 v181, v163, v177
	s_waitcnt lgkmcnt(0)
	v_add_f32_e32 v174, v174, v178
	v_add_f32_e32 v175, v175, v179
	v_add_f32_e32 v176, v176, v180
	v_add_f32_e32 v177, v177, v181
	ds_bpermute_b32 v178, v164, v174
	ds_bpermute_b32 v179, v164, v175
	ds_bpermute_b32 v180, v164, v176
	ds_bpermute_b32 v181, v164, v177
	s_waitcnt lgkmcnt(0)
	v_add_f32_e32 v174, v174, v178
	v_add_f32_e32 v175, v175, v179
	v_add_f32_e32 v176, v176, v180
	v_add_f32_e32 v177, v177, v181
	ds_bpermute_b32 v178, v165, v174
	ds_bpermute_b32 v179, v165, v175
	ds_bpermute_b32 v180, v165, v176
	ds_bpermute_b32 v181, v165, v177
	s_waitcnt lgkmcnt(0)
	v_add_f32_e32 v174, v174, v178
	v_add_f32_e32 v175, v175, v179
	v_add_f32_e32 v176, v176, v180
	v_add_f32_e32 v177, v177, v181
	v_fmaak_f32 v174, v228, v174, 0x358637bd
	v_fmaak_f32 v175, v228, v175, 0x358637bd
	v_fmaak_f32 v176, v228, v176, 0x358637bd
	v_fmaak_f32 v177, v228, v177, 0x358637bd
	v_rsq_f32_e32 v182, v174
	v_rsq_f32_e32 v183, v175
	v_rsq_f32_e32 v184, v176
	v_rsq_f32_e32 v185, v177
	s_waitcnt vmcnt(0)
	s_cmp_eq_u32 s18, 1
	s_cbranch_scc1 .Lmy_ln1_final
	v_add_f32_e32 v144, 1.0, v144
	v_add_f32_e32 v145, 1.0, v145
	v_add_f32_e32 v146, 1.0, v146
	v_add_f32_e32 v147, 1.0, v147
	v_add_f32_e32 v148, 1.0, v148
	v_add_f32_e32 v149, 1.0, v149
	v_add_f32_e32 v150, 1.0, v150
	v_add_f32_e32 v151, 1.0, v151
	v_add_f32_e32 v152, 1.0, v152
	v_add_f32_e32 v153, 1.0, v153
	v_add_f32_e32 v154, 1.0, v154
	v_add_f32_e32 v155, 1.0, v155
	v_add_f32_e32 v156, 1.0, v156
	v_add_f32_e32 v157, 1.0, v157
	v_add_f32_e32 v158, 1.0, v158
	v_add_f32_e32 v159, 1.0, v159
	v_mul_f32_e32 v0, v0, v182
	v_mul_f32_e32 v1, v1, v182
	v_mul_f32_e32 v2, v2, v182
	v_mul_f32_e32 v3, v3, v182
	v_fma_f32 v0, v0, v96, v112
	v_fma_f32 v1, v1, v97, v113
	v_fma_f32 v2, v2, v98, v114
	v_fma_f32 v3, v3, v99, v115
	global_store_dwordx4 v218, v[0:3], s[94:95] nt sc1
	v_fma_f32 v224, v0, v144, v128
	v_fma_f32 v225, v1, v145, v129
	v_fma_f32 v226, v2, v146, v130
	v_fma_f32 v227, v3, v147, v131
	v_cvt_pk_bf16_f32 v232, v224, v225
	v_cvt_pk_bf16_f32 v233, v226, v227
	global_store_dwordx2 v222, v[232:233], s[94:95] nt sc1
	v_mul_f32_e32 v4, v4, v182
	v_mul_f32_e32 v5, v5, v182
	v_mul_f32_e32 v6, v6, v182
	v_mul_f32_e32 v7, v7, v182
	v_fma_f32 v4, v4, v100, v116
	v_fma_f32 v5, v5, v101, v117
	v_fma_f32 v6, v6, v102, v118
	v_fma_f32 v7, v7, v103, v119
	global_store_dwordx4 v218, v[4:7], s[94:95] offset:1024 nt sc1
	v_fma_f32 v224, v4, v148, v132
	v_fma_f32 v225, v5, v149, v133
	v_fma_f32 v226, v6, v150, v134
	v_fma_f32 v227, v7, v151, v135
	v_cvt_pk_bf16_f32 v232, v224, v225
	v_cvt_pk_bf16_f32 v233, v226, v227
	global_store_dwordx2 v222, v[232:233], s[94:95] offset:512 nt sc1
	v_mul_f32_e32 v8, v8, v182
	v_mul_f32_e32 v9, v9, v182
	v_mul_f32_e32 v10, v10, v182
; DI unsigned pk2(float a, float b) { f32x2 v = {a, b}; bfx2 r = __builtin_convertvector(v, bfx2); return __builtin_bit_cast(unsigned, r); }
; template <int NR>
; DI void ln_rows(const Params& P, const LnSpec& sp, int row, int stride, int lane) {
;     ...
;     for (int k = 0; k < NR; ++k) {
;         const int r = row + k * stride;
;         const float mu = s[k], rstd = rsqrtf(qv[k] * (1.f / 1024.f) + 1e-6f);
;         const int sidx = r < RL ? (r >> 13) : 4;
;         const float* sh = MOD + (size_t)(sp.lnext * 5 + sidx) * 9216 + sp.mshift * 1024; const float* scl = sh + 1024;
;         float* xp = X + (size_t)r * 1024;
; #pragma unroll
;         for (int i = 0; i < 4; ++i) {
;             const int c = (i * 64 + lane) * 4;
;             const f32x4 gg = *(const f32x4*)(g + c), b4 = *(const f32x4*)(bb + c);
;             f32x4 y;
; #pragma unroll
;             for (int j = 0; j < 4; ++j) y[j] = (v[k][i][j] - mu) * rstd * gg[j] + b4[j];
;             if (sp.final_) { __builtin_nontemporal_store(y, (f32x4*)(P.out + (size_t)r * 1024 + c)); }
;             else {
;                 __builtin_nontemporal_store(y, (f32x4*)(xp + c));
;                 const f32x4 a = *(const f32x4*)(sh + c), sg = *(const f32x4*)(scl + c);
;                 u32x2 w; w.x = pk2(y[0] * (1.f + sg[0]) + a[0], y[1] * (1.f + sg[1]) + a[1]); w.y = pk2(y[2] * (1.f + sg[2]) + a[2], y[3] * (1.f + sg[3]) + a[3]);
;                 *(u32x2*)(XM + (size_t)r * 1024 + c) = w;
;             }
;         }
;     }
	v_mul_f32_e32 v11, v11, v182
	v_fma_f32 v8, v8, v104, v120
	v_fma_f32 v9, v9, v105, v121
	v_fma_f32 v10, v10, v106, v122
	v_fma_f32 v11, v11, v107, v123
	global_store_dwordx4 v218, v[8:11], s[94:95] offset:2048 nt sc1
	v_fma_f32 v224, v8, v152, v136
	v_fma_f32 v225, v9, v153, v137
	v_fma_f32 v226, v10, v154, v138
	v_fma_f32 v227, v11, v155, v139
	v_cvt_pk_bf16_f32 v232, v224, v225
	v_cvt_pk_bf16_f32 v233, v226, v227
	global_store_dwordx2 v222, v[232:233], s[94:95] offset:1024 nt sc1
	v_mul_f32_e32 v12, v12, v182
	v_mul_f32_e32 v13, v13, v182
	v_mul_f32_e32 v14, v14, v182
	v_mul_f32_e32 v15, v15, v182
	v_fma_f32 v12, v12, v108, v124
	v_fma_f32 v13, v13, v109, v125
	v_fma_f32 v14, v14, v110, v126
	v_fma_f32 v15, v15, v111, v127
	global_store_dwordx4 v218, v[12:15], s[94:95] offset:3072 nt sc1
	v_fma_f32 v224, v12, v156, v140
	v_fma_f32 v225, v13, v157, v141
	v_fma_f32 v226, v14, v158, v142
	v_fma_f32 v227, v15, v159, v143
	v_cvt_pk_bf16_f32 v232, v224, v225
	v_cvt_pk_bf16_f32 v233, v226, v227
	global_store_dwordx2 v222, v[232:233], s[94:95] offset:1536 nt sc1
	v_mul_f32_e32 v16, v16, v183
	v_mul_f32_e32 v17, v17, v183
	v_mul_f32_e32 v18, v18, v183
	v_mul_f32_e32 v19, v19, v183
	v_fma_f32 v16, v16, v96, v112
	v_fma_f32 v17, v17, v97, v113
	v_fma_f32 v18, v18, v98, v114
	v_fma_f32 v19, v19, v99, v115
	global_store_dwordx4 v219, v[16:19], s[94:95] nt sc1
	v_fma_f32 v224, v16, v144, v128
	v_fma_f32 v225, v17, v145, v129
	v_fma_f32 v226, v18, v146, v130
	v_fma_f32 v227, v19, v147, v131
	v_cvt_pk_bf16_f32 v232, v224, v225
	v_cvt_pk_bf16_f32 v233, v226, v227
	global_store_dwordx2 v222, v[232:233], s[94:95] offset:2048 nt sc1
	v_mul_f32_e32 v20, v20, v183
	v_mul_f32_e32 v21, v21, v183
	v_mul_f32_e32 v22, v22, v183
	v_mul_f32_e32 v23, v23, v183
	v_fma_f32 v20, v20, v100, v116
	v_fma_f32 v21, v21, v101, v117
	v_fma_f32 v22, v22, v102, v118
	v_fma_f32 v23, v23, v103, v119
	global_store_dwordx4 v219, v[20:23], s[94:95] offset:1024 nt sc1
	v_fma_f32 v224, v20, v148, v132
	v_fma_f32 v225, v21, v149, v133
	v_fma_f32 v226, v22, v150, v134
	v_fma_f32 v227, v23, v151, v135
	v_cvt_pk_bf16_f32 v232, v224, v225
	v_cvt_pk_bf16_f32 v233, v226, v227
	global_store_dwordx2 v222, v[232:233], s[94:95] offset:2560 nt sc1
	v_mul_f32_e32 v24, v24, v183
	v_mul_f32_e32 v25, v25, v183
	v_mul_f32_e32 v26, v26, v183
	v_mul_f32_e32 v27, v27, v183
	v_fma_f32 v24, v24, v104, v120
	v_fma_f32 v25, v25, v105, v121
	v_fma_f32 v26, v26, v106, v122
	v_fma_f32 v27, v27, v107, v123
	global_store_dwordx4 v219, v[24:27], s[94:95] offset:2048 nt sc1
	v_fma_f32 v224, v24, v152, v136
	v_fma_f32 v225, v25, v153, v137
	v_fma_f32 v226, v26, v154, v138
	v_fma_f32 v227, v27, v155, v139
	v_cvt_pk_bf16_f32 v232, v224, v225
	v_cvt_pk_bf16_f32 v233, v226, v227
	global_store_dwordx2 v222, v[232:233], s[94:95] offset:3072 nt sc1
	v_mul_f32_e32 v28, v28, v183
	v_mul_f32_e32 v29, v29, v183
	v_mul_f32_e32 v30, v30, v183
	v_mul_f32_e32 v31, v31, v183
	v_fma_f32 v28, v28, v108, v124
	v_fma_f32 v29, v29, v109, v125
	v_fma_f32 v30, v30, v110, v126
	v_fma_f32 v31, v31, v111, v127
	global_store_dwordx4 v219, v[28:31], s[94:95] offset:3072 nt sc1
	v_fma_f32 v224, v28, v156, v140
	v_fma_f32 v225, v29, v157, v141
	v_fma_f32 v226, v30, v158, v142
	v_fma_f32 v227, v31, v159, v143
	v_cvt_pk_bf16_f32 v232, v224, v225
	v_cvt_pk_bf16_f32 v233, v226, v227
	global_store_dwordx2 v222, v[232:233], s[94:95] offset:3584 nt sc1
	v_mul_f32_e32 v32, v32, v184
	v_mul_f32_e32 v33, v33, v184
	v_mul_f32_e32 v34, v34, v184
	v_mul_f32_e32 v35, v35, v184
	v_fma_f32 v32, v32, v96, v112
	v_fma_f32 v33, v33, v97, v113
	v_fma_f32 v34, v34, v98, v114
	v_fma_f32 v35, v35, v99, v115
	global_store_dwordx4 v220, v[32:35], s[94:95] nt sc1
	v_fma_f32 v224, v32, v144, v128
	v_fma_f32 v225, v33, v145, v129
	v_fma_f32 v226, v34, v146, v130
	v_fma_f32 v227, v35, v147, v131
	v_cvt_pk_bf16_f32 v232, v224, v225
	v_cvt_pk_bf16_f32 v233, v226, v227
	global_store_dwordx2 v223, v[232:233], s[94:95] nt sc1
	v_mul_f32_e32 v36, v36, v184
	v_mul_f32_e32 v37, v37, v184
; DI unsigned pk2(float a, float b) { f32x2 v = {a, b}; bfx2 r = __builtin_convertvector(v, bfx2); return __builtin_bit_cast(unsigned, r); }
; template <int NR>
; DI void ln_rows(const Params& P, const LnSpec& sp, int row, int stride, int lane) {
;     ...
;     for (int k = 0; k < NR; ++k) {
;         const int r = row + k * stride;
;         const float mu = s[k], rstd = rsqrtf(qv[k] * (1.f / 1024.f) + 1e-6f);
;         const int sidx = r < RL ? (r >> 13) : 4;
;         const float* sh = MOD + (size_t)(sp.lnext * 5 + sidx) * 9216 + sp.mshift * 1024; const float* scl = sh + 1024;
;         float* xp = X + (size_t)r * 1024;
; #pragma unroll
;         for (int i = 0; i < 4; ++i) {
;             const int c = (i * 64 + lane) * 4;
;             const f32x4 gg = *(const f32x4*)(g + c), b4 = *(const f32x4*)(bb + c);
;             f32x4 y;
; #pragma unroll
;             for (int j = 0; j < 4; ++j) y[j] = (v[k][i][j] - mu) * rstd * gg[j] + b4[j];
;             if (sp.final_) { __builtin_nontemporal_store(y, (f32x4*)(P.out + (size_t)r * 1024 + c)); }
;             else {
;                 __builtin_nontemporal_store(y, (f32x4*)(xp + c));
;                 const f32x4 a = *(const f32x4*)(sh + c), sg = *(const f32x4*)(scl + c);
;                 u32x2 w; w.x = pk2(y[0] * (1.f + sg[0]) + a[0], y[1] * (1.f + sg[1]) + a[1]); w.y = pk2(y[2] * (1.f + sg[2]) + a[2], y[3] * (1.f + sg[3]) + a[3]);
;                 *(u32x2*)(XM + (size_t)r * 1024 + c) = w;
;             }
;         }
;     }
	v_mul_f32_e32 v38, v38, v184
	v_mul_f32_e32 v39, v39, v184
	v_fma_f32 v36, v36, v100, v116
	v_fma_f32 v37, v37, v101, v117
	v_fma_f32 v38, v38, v102, v118
	v_fma_f32 v39, v39, v103, v119
	global_store_dwordx4 v220, v[36:39], s[94:95] offset:1024 nt sc1
	v_fma_f32 v224, v36, v148, v132
	v_fma_f32 v225, v37, v149, v133
	v_fma_f32 v226, v38, v150, v134
	v_fma_f32 v227, v39, v151, v135
	v_cvt_pk_bf16_f32 v232, v224, v225
	v_cvt_pk_bf16_f32 v233, v226, v227
	global_store_dwordx2 v223, v[232:233], s[94:95] offset:512 nt sc1
	v_mul_f32_e32 v40, v40, v184
	v_mul_f32_e32 v41, v41, v184
	v_mul_f32_e32 v42, v42, v184
	v_mul_f32_e32 v43, v43, v184
	v_fma_f32 v40, v40, v104, v120
	v_fma_f32 v41, v41, v105, v121
	v_fma_f32 v42, v42, v106, v122
	v_fma_f32 v43, v43, v107, v123
	global_store_dwordx4 v220, v[40:43], s[94:95] offset:2048 nt sc1
	v_fma_f32 v224, v40, v152, v136
	v_fma_f32 v225, v41, v153, v137
	v_fma_f32 v226, v42, v154, v138
	v_fma_f32 v227, v43, v155, v139
	v_cvt_pk_bf16_f32 v232, v224, v225
	v_cvt_pk_bf16_f32 v233, v226, v227
	global_store_dwordx2 v223, v[232:233], s[94:95] offset:1024 nt sc1
	v_mul_f32_e32 v44, v44, v184
	v_mul_f32_e32 v45, v45, v184
	v_mul_f32_e32 v46, v46, v184
	v_mul_f32_e32 v47, v47, v184
	v_fma_f32 v44, v44, v108, v124
	v_fma_f32 v45, v45, v109, v125
	v_fma_f32 v46, v46, v110, v126
	v_fma_f32 v47, v47, v111, v127
	global_store_dwordx4 v220, v[44:47], s[94:95] offset:3072 nt sc1
	v_fma_f32 v224, v44, v156, v140
	v_fma_f32 v225, v45, v157, v141
	v_fma_f32 v226, v46, v158, v142
	v_fma_f32 v227, v47, v159, v143
	v_cvt_pk_bf16_f32 v232, v224, v225
	v_cvt_pk_bf16_f32 v233, v226, v227
	global_store_dwordx2 v223, v[232:233], s[94:95] offset:1536 nt sc1
	v_mul_f32_e32 v48, v48, v185
	v_mul_f32_e32 v49, v49, v185
	v_mul_f32_e32 v50, v50, v185
	v_mul_f32_e32 v51, v51, v185
	v_fma_f32 v48, v48, v96, v112
	v_fma_f32 v49, v49, v97, v113
	v_fma_f32 v50, v50, v98, v114
	v_fma_f32 v51, v51, v99, v115
	global_store_dwordx4 v221, v[48:51], s[94:95] nt sc1
	v_fma_f32 v224, v48, v144, v128
	v_fma_f32 v225, v49, v145, v129
	v_fma_f32 v226, v50, v146, v130
	v_fma_f32 v227, v51, v147, v131
	v_cvt_pk_bf16_f32 v232, v224, v225
	v_cvt_pk_bf16_f32 v233, v226, v227
	global_store_dwordx2 v223, v[232:233], s[94:95] offset:2048 nt sc1
	v_mul_f32_e32 v52, v52, v185
	v_mul_f32_e32 v53, v53, v185
	v_mul_f32_e32 v54, v54, v185
	v_mul_f32_e32 v55, v55, v185
	v_fma_f32 v52, v52, v100, v116
	v_fma_f32 v53, v53, v101, v117
	v_fma_f32 v54, v54, v102, v118
	v_fma_f32 v55, v55, v103, v119
	global_store_dwordx4 v221, v[52:55], s[94:95] offset:1024 nt sc1
	v_fma_f32 v224, v52, v148, v132
	v_fma_f32 v225, v53, v149, v133
	v_fma_f32 v226, v54, v150, v134
	v_fma_f32 v227, v55, v151, v135
	v_cvt_pk_bf16_f32 v232, v224, v225
	v_cvt_pk_bf16_f32 v233, v226, v227
	global_store_dwordx2 v223, v[232:233], s[94:95] offset:2560 nt sc1
	v_mul_f32_e32 v56, v56, v185
	v_mul_f32_e32 v57, v57, v185
	v_mul_f32_e32 v58, v58, v185
	v_mul_f32_e32 v59, v59, v185
	v_fma_f32 v56, v56, v104, v120
	v_fma_f32 v57, v57, v105, v121
	v_fma_f32 v58, v58, v106, v122
	v_fma_f32 v59, v59, v107, v123
	global_store_dwordx4 v221, v[56:59], s[94:95] offset:2048 nt sc1
	v_fma_f32 v224, v56, v152, v136
	v_fma_f32 v225, v57, v153, v137
	v_fma_f32 v226, v58, v154, v138
	v_fma_f32 v227, v59, v155, v139
	v_cvt_pk_bf16_f32 v232, v224, v225
	v_cvt_pk_bf16_f32 v233, v226, v227
	global_store_dwordx2 v223, v[232:233], s[94:95] offset:3072 nt sc1
	v_mul_f32_e32 v60, v60, v185
	v_mul_f32_e32 v61, v61, v185
	v_mul_f32_e32 v62, v62, v185
	v_mul_f32_e32 v63, v63, v185
	v_fma_f32 v60, v60, v108, v124
	v_fma_f32 v61, v61, v109, v125
	v_fma_f32 v62, v62, v110, v126
	v_fma_f32 v63, v63, v111, v127
	global_store_dwordx4 v221, v[60:63], s[94:95] offset:3072 nt sc1
	v_fma_f32 v224, v60, v156, v140
	v_fma_f32 v225, v61, v157, v141
	v_fma_f32 v226, v62, v158, v142
	v_fma_f32 v227, v63, v159, v143
	v_cvt_pk_bf16_f32 v232, v224, v225
	v_cvt_pk_bf16_f32 v233, v226, v227
	global_store_dwordx2 v223, v[232:233], s[94:95] offset:3584 nt sc1
	s_branch .Lmy_ln1_next
